# v14_ldearly
# baseline (speedup 1.0000x reference)
; #define MFMA32(a, b, c) __builtin_amdgcn_mfma_f32_32x32x16_bf16((a), (b), (c), 0, 0, 0)
; DI f32x16 zero16() { f32x16 z; for (int i = 0; i < 16; ++i) z[i] = 0.f; return z; }
; template <int DQK, int MODE>
; DI void attn_core(const u16* __restrict__ Qg, int ldq, const u16* __restrict__ Kg, int ldk, const u16* __restrict__ Vtg,
;                   const u64* __restrict__ maskg, int q0, float scale, char* smem, int* sflags, f32x16 (&o)[4], float& l_run) {
;     ...
;   for (int it = 0; it < ntiles; ++it, tau += step) {
;     __syncthreads();
;     if (MODE == 2 && it > 0) {
;       if (!(sflags[0] | sflags[1] | sflags[2] | sflags[3] | sflags[4] | sflags[5] | sflags[6] | sflags[7])) break;
;     }
;     if (MODE == 2) gload(tau);
; #pragma unroll
;     for (int i = 0; i < NVK; ++i) {
;       const int v = tid + NT * i, row = v / VPR, c = v % VPR;
;       *(u32x4*)(Ks + row * KSTR + c * 8) = rk[i];
;     }
; #pragma unroll
;     for (int i = 0; i < 2; ++i) {
;       const int v = tid + NT * i, row = v >> 3, c = v & 7;
;       *(u32x4*)(Vs + row * 72 + c * 8) = rv[i];
;     }
;     __syncthreads();
;     if (MODE != 2 && it + 1 < ntiles) gload(tau + step);
;     if (tau * 64 > q0 + 32 * wid + 31) {
;       if (MODE == 2 && lane == 0) sflags[wid] = 1;
;       continue;
;     }
;     u64 mbits = 0;
;     if (MODE == 1) mbits = maskg[(long)qrow * 64 + tau] >> (8 * hh);
;     f32x16 s[2];
;     s[0] = zero16(); s[1] = zero16();
; #pragma unroll
;     for (int kt = 0; kt < 2; ++kt)
; #pragma unroll
;       for (int ks = 0; ks < NKS; ++ks) {
;         const bf16x8 kf = *(const bf16x8*)(Ks + (32 * kt + krow) * KSTR + ks * 16 + hh * 8);
;         s[kt] = MFMA32(kf, qf[ks], s[kt]);
;       }
.LBB0_156:
	v_add_u32_e32 v0, s0, v176
	v_mad_i64_i32 v[2:3], s[4:5], v0, s75, v[168:169]
	v_add_u32_e32 v0, s0, v177
	v_mad_i64_i32 v[4:5], s[4:5], v0, s75, v[170:171]
	s_ashr_i32 s1, s0, 31
	s_lshl_b64 s[4:5], s[0:1], 1
	s_nop 0
	s_waitcnt vmcnt(0)
	ds_write_b128 v180, v[156:159]
	ds_write_b128 v181, v[152:155]
	ds_write_b128 v182, v[148:151] offset:17408
	ds_write_b128 v183, v[144:147] offset:17408
	s_waitcnt lgkmcnt(0)
	global_load_dwordx4 v[156:159], v[2:3], off
	global_load_dwordx4 v[152:155], v[4:5], off
	v_lshl_add_u64 v[2:3], v[162:163], 0, s[4:5]
	v_lshl_add_u64 v[4:5], v[166:167], 0, s[4:5]
	global_load_dwordx4 v[148:151], v[2:3], off
	global_load_dwordx4 v[144:147], v[4:5], off
	s_sub_i32 s1, s0, 64
	s_barrier
	v_cmp_le_i32_e32 vcc, s1, v179
	s_and_saveexec_b64 s[4:5], vcc
	s_cbranch_execz .LBB0_155
	v_add_u32_e32 v0, v174, v178
	global_load_dwordx2 v[10:11], v[172:173], off
	ds_read_b128 v[12:15], v0
	ds_read_b128 v[202:205], v0 offset:32
	ds_read_b128 v[210:213], v0 offset:64
	ds_read_b128 v[214:217], v0 offset:96
	ds_read_b128 v[218:221], v0 offset:128
	ds_read_b128 v[226:229], v0 offset:160
	s_waitcnt lgkmcnt(5)
	v_mfma_f32_32x32x16_bf16 v[96:111], v[12:15], v[140:143], 0
	ds_read_b128 v[12:15], v0 offset:192
	s_waitcnt lgkmcnt(5)
	v_mfma_f32_32x32x16_bf16 v[96:111], v[202:205], v[136:139], v[96:111]
	ds_read_b128 v[202:205], v0 offset:224
	s_waitcnt vmcnt(0)
	v_lshrrev_b64 v[8:9], v160, v[10:11]
	s_waitcnt lgkmcnt(5)
	v_mfma_f32_32x32x16_bf16 v[96:111], v[210:213], v[132:135], v[96:111]
	ds_read_b128 v[210:213], v0 offset:8704
	s_waitcnt lgkmcnt(5)
	v_mfma_f32_32x32x16_bf16 v[96:111], v[214:217], v[128:131], v[96:111]
	ds_read_b128 v[214:217], v0 offset:8736
	s_waitcnt lgkmcnt(5)
	v_mfma_f32_32x32x16_bf16 v[96:111], v[218:221], v[124:127], v[96:111]
	ds_read_b128 v[218:221], v0 offset:8768
	s_waitcnt lgkmcnt(5)
	v_mfma_f32_32x32x16_bf16 v[96:111], v[226:229], v[120:123], v[96:111]
	ds_read_b128 v[226:229], v0 offset:8800
	s_waitcnt lgkmcnt(5)
	v_mfma_f32_32x32x16_bf16 v[96:111], v[12:15], v[116:119], v[96:111]
	ds_read_b128 v[12:15], v0 offset:8832
	s_waitcnt lgkmcnt(5)
	v_mfma_f32_32x32x16_bf16 v[96:111], v[202:205], v[112:115], v[96:111]
	ds_read_b128 v[202:205], v0 offset:8864
	s_waitcnt lgkmcnt(5)
	v_mfma_f32_32x32x16_bf16 v[80:95], v[210:213], v[140:143], 0
	ds_read_b128 v[210:213], v0 offset:8896
	s_waitcnt lgkmcnt(5)
	v_mfma_f32_32x32x16_bf16 v[80:95], v[214:217], v[136:139], v[80:95]
	ds_read_b128 v[214:217], v0 offset:8928
	s_waitcnt lgkmcnt(5)
	v_mfma_f32_32x32x16_bf16 v[80:95], v[218:221], v[132:135], v[80:95]
	s_waitcnt lgkmcnt(4)
	v_mfma_f32_32x32x16_bf16 v[80:95], v[226:229], v[128:131], v[80:95]
	s_waitcnt lgkmcnt(3)
	v_mfma_f32_32x32x16_bf16 v[80:95], v[12:15], v[124:127], v[80:95]
	s_waitcnt lgkmcnt(2)
	v_mfma_f32_32x32x16_bf16 v[80:95], v[202:205], v[120:123], v[80:95]
	s_waitcnt lgkmcnt(1)
	v_mfma_f32_32x32x16_bf16 v[80:95], v[210:213], v[116:119], v[80:95]
	v_lshrrev_b32_e32 v0, v160, v10
	v_and_b32_e32 v0, 1, v0
	v_cmp_eq_u32_e32 vcc, 1, v0
	v_and_b32_e32 v0, 2, v8
	s_nop 0
	v_cndmask_b32_e32 v200, v225, v96, vcc
	v_cmp_ne_u32_e32 vcc, 0, v0
	v_and_b32_e32 v0, 4, v8
	s_waitcnt lgkmcnt(0)
; template <int DQK, int MODE>
; DI void attn_core(const u16* __restrict__ Qg, int ldq, const u16* __restrict__ Kg, int ldk, const u16* __restrict__ Vtg,
;                   const u64* __restrict__ maskg, int q0, float scale, char* smem, int* sflags, f32x16 (&o)[4], float& l_run) {
;     ...
;       float mx = -1e30f;
;       if (need_mask) {
; #pragma unroll
;         for (int kt = 0; kt < 2; ++kt)
; #pragma unroll
;           for (int i = 0; i < 16; ++i) {
;             bool valid;
;             if (MODE == 1) valid = (mbits >> (32 * kt + 16 * (i >> 3) + (i & 7))) & 1ull;
;             else valid = (kbase + 32 * kt + 16 * (i >> 3) + (i & 7)) <= qrow;
;             s[kt][i] = valid ? s[kt][i] : -1e30f;
;           }
;       }
; #pragma unroll
;       for (int kt = 0; kt < 2; ++kt)
; #pragma unroll
;         for (int i = 0; i < 16; ++i) mx = fmaxf(mx, s[kt][i]);
;       mx = fmaxf(mx, __shfl_xor(mx, 32));
;       const float m_new = fmaxf(m_run, mx);
;       const float alpha = __builtin_amdgcn_exp2f((m_run - m_new) * sc);
;       m_run = m_new;
;       const float msc = -m_new * sc;
;       float ls = 0.f;
; #pragma unroll
;       for (int kt = 0; kt < 2; ++kt)
; #pragma unroll
;         for (int i = 0; i < 16; ++i) {
;           float pv = __builtin_amdgcn_exp2f(__builtin_fmaf(s[kt][i], sc, msc));
;           if (MODE == 1) pv = (s[kt][i] > -1e29f) ? pv : 0.f;
;           s[kt][i] = pv;
;           ls += pv;
;         }
;       if (__any(alpha != 1.0f)) {
;         l_run *= alpha;
; #pragma unroll
;         for (int t = 0; t < 4; ++t)
; #pragma unroll
;           for (int i = 0; i < 16; ++i) o[t][i] *= alpha;
;       }
	v_mfma_f32_32x32x16_bf16 v[80:95], v[214:217], v[112:115], v[80:95]
	v_cndmask_b32_e32 v187, v225, v97, vcc
	v_cmp_ne_u32_e32 vcc, 0, v0
	v_and_b32_e32 v0, 8, v8
	v_mbcnt_hi_u32_b32 v2, -1, v223
	v_cndmask_b32_e32 v199, v225, v98, vcc
	v_cmp_ne_u32_e32 vcc, 0, v0
	v_and_b32_e32 v0, 16, v8
	s_nop 0
	v_cndmask_b32_e32 v198, v225, v99, vcc
	v_cmp_ne_u32_e32 vcc, 0, v0
	v_and_b32_e32 v0, 32, v8
	s_nop 0
	v_cndmask_b32_e32 v201, v225, v100, vcc
	v_cmp_ne_u32_e32 vcc, 0, v0
	v_and_b32_e32 v0, 64, v8
	s_nop 0
	v_cndmask_b32_e32 v96, v225, v101, vcc
	v_cmp_ne_u32_e32 vcc, 0, v0
	v_and_b32_e32 v0, 0x80, v8
	s_nop 0
	v_cndmask_b32_e32 v186, v225, v102, vcc
	v_cmp_ne_u32_e32 vcc, 0, v0
	v_and_b32_e32 v0, 0x10000, v8
	s_nop 0
	v_cndmask_b32_e32 v97, v225, v103, vcc
	v_cmp_ne_u32_e32 vcc, 0, v0
	v_and_b32_e32 v0, 0x20000, v8
	s_nop 0
	v_cndmask_b32_e32 v185, v225, v104, vcc
	v_cmp_ne_u32_e32 vcc, 0, v0
	v_and_b32_e32 v0, 0x40000, v8
	s_nop 0
	v_cndmask_b32_e32 v105, v225, v105, vcc
	v_cmp_ne_u32_e32 vcc, 0, v0
	v_and_b32_e32 v0, 0x80000, v8
	s_nop 0
	v_cndmask_b32_e32 v104, v225, v106, vcc
	v_cmp_ne_u32_e32 vcc, 0, v0
	v_and_b32_e32 v0, 0x100000, v8
	s_nop 0
	v_cndmask_b32_e32 v103, v225, v107, vcc
	v_cmp_ne_u32_e32 vcc, 0, v0
	v_and_b32_e32 v0, 0x200000, v8
	s_nop 0
	v_cndmask_b32_e32 v102, v225, v108, vcc
	v_cmp_ne_u32_e32 vcc, 0, v0
	v_and_b32_e32 v0, 0x400000, v8
	s_nop 0
	v_cndmask_b32_e32 v10, v225, v109, vcc
	v_cmp_ne_u32_e32 vcc, 0, v0
	v_and_b32_e32 v0, 0x800000, v8
	s_nop 0
	v_cndmask_b32_e32 v100, v225, v110, vcc
	v_cmp_ne_u32_e32 vcc, 0, v0
	v_and_b32_e32 v0, 1, v9
	s_nop 0
	v_cndmask_b32_e32 v11, v225, v111, vcc
	v_cmp_eq_u32_e32 vcc, 1, v0
	v_and_b32_e32 v0, 2, v9
	s_nop 0
	v_cndmask_b32_e32 v101, v225, v80, vcc
	v_cmp_ne_u32_e32 vcc, 0, v0
	v_and_b32_e32 v0, 4, v9
	s_nop 0
	v_cndmask_b32_e32 v99, v225, v81, vcc
	v_cmp_ne_u32_e32 vcc, 0, v0
	v_and_b32_e32 v0, 8, v9
	s_nop 0
	v_cndmask_b32_e32 v12, v225, v82, vcc
	v_cmp_ne_u32_e32 vcc, 0, v0
	v_and_b32_e32 v0, 16, v9
	v_xor_b32_e32 v82, 32, v2
	v_cndmask_b32_e32 v13, v225, v83, vcc
	v_cmp_ne_u32_e32 vcc, 0, v0
	v_and_b32_e32 v0, 32, v9
	v_and_b32_e32 v83, 64, v2
	v_cndmask_b32_e32 v14, v225, v84, vcc
	v_cmp_ne_u32_e32 vcc, 0, v0
	v_and_b32_e32 v0, 64, v9
	v_add_u32_e32 v83, 64, v83
	v_cndmask_b32_e32 v15, v225, v85, vcc
	v_cmp_ne_u32_e32 vcc, 0, v0
	v_and_b32_e32 v0, 0x80, v9
	s_nop 0
	v_cndmask_b32_e32 v80, v225, v86, vcc
	v_cmp_ne_u32_e32 vcc, 0, v0
	v_and_b32_e32 v0, 0x10000, v9
	s_nop 0
	v_cndmask_b32_e32 v81, v225, v87, vcc
	v_cmp_ne_u32_e32 vcc, 0, v0
	v_and_b32_e32 v0, 0x20000, v9
	s_nop 0
	v_cndmask_b32_e32 v98, v225, v88, vcc
	v_cmp_ne_u32_e32 vcc, 0, v0
	v_and_b32_e32 v0, 0x40000, v9
	s_nop 0
	v_cndmask_b32_e32 v3, v225, v89, vcc
	v_cmp_ne_u32_e32 vcc, 0, v0
	v_and_b32_e32 v0, 0x80000, v9
	s_nop 0
	v_cndmask_b32_e32 v4, v225, v90, vcc
	v_cmp_ne_u32_e32 vcc, 0, v0
	v_and_b32_e32 v0, 0x100000, v9
	s_nop 0
	v_cndmask_b32_e32 v5, v225, v91, vcc
	v_cmp_ne_u32_e32 vcc, 0, v0
	v_and_b32_e32 v0, 0x200000, v9
	s_nop 0
	v_cndmask_b32_e32 v6, v225, v92, vcc
	v_cmp_ne_u32_e32 vcc, 0, v0
	v_and_b32_e32 v0, 0x400000, v9
	s_nop 0
	v_cndmask_b32_e32 v7, v225, v93, vcc
	v_cmp_ne_u32_e32 vcc, 0, v0
	v_and_b32_e32 v0, 0x800000, v9
	s_nop 0
	v_cndmask_b32_e32 v8, v225, v94, vcc
	v_cmp_ne_u32_e32 vcc, 0, v0
	v_max3_f32 v0, v200, s58, v187
	v_max3_f32 v0, v0, v199, v198
	v_max3_f32 v0, v0, v201, v96
	v_max3_f32 v0, v0, v186, v97
	v_max3_f32 v0, v0, v185, v105
	v_max3_f32 v0, v0, v104, v103
	v_max3_f32 v0, v0, v102, v10
	v_max3_f32 v0, v0, v100, v11
	v_max3_f32 v0, v0, v101, v99
	v_max3_f32 v0, v0, v12, v13
	v_max3_f32 v0, v0, v14, v15
	v_max3_f32 v0, v0, v80, v81
	v_max3_f32 v0, v0, v98, v3
	v_cndmask_b32_e32 v9, v225, v95, vcc
	v_max3_f32 v0, v0, v4, v5
	v_cmp_lt_i32_e32 vcc, v82, v83
	v_max3_f32 v0, v0, v6, v7
	v_max3_f32 v0, v0, v8, v9
	v_cndmask_b32_e32 v2, v2, v82, vcc
	v_lshlrev_b32_e32 v2, 2, v2
	ds_bpermute_b32 v2, v2, v0
	s_waitcnt lgkmcnt(0)
	v_max3_f32 v2, v184, v0, v2
	v_sub_f32_e32 v0, v184, v2
	v_mul_f32_e32 v0, 0x3e0293ee, v0
	v_exp_f32_e32 v0, v0
	s_nop 0
	v_cmp_neq_f32_e32 vcc, 1.0, v0
	s_cbranch_vccz .LBB0_154
	v_mul_f32_e32 v161, v161, v0
	v_pk_mul_f32 v[78:79], v[0:1], v[78:79] op_sel_hi:[0,1]
	v_pk_mul_f32 v[76:77], v[0:1], v[76:77] op_sel_hi:[0,1]
	v_pk_mul_f32 v[74:75], v[0:1], v[74:75] op_sel_hi:[0,1]
	v_pk_mul_f32 v[72:73], v[0:1], v[72:73] op_sel_hi:[0,1]
	v_pk_mul_f32 v[70:71], v[0:1], v[70:71] op_sel_hi:[0,1]
	v_pk_mul_f32 v[68:69], v[0:1], v[68:69] op_sel_hi:[0,1]
	v_pk_mul_f32 v[66:67], v[0:1], v[66:67] op_sel_hi:[0,1]
	v_pk_mul_f32 v[64:65], v[0:1], v[64:65] op_sel_hi:[0,1]
	v_pk_mul_f32 v[62:63], v[0:1], v[62:63] op_sel_hi:[0,1]
	v_pk_mul_f32 v[60:61], v[0:1], v[60:61] op_sel_hi:[0,1]
	v_pk_mul_f32 v[58:59], v[0:1], v[58:59] op_sel_hi:[0,1]
	v_pk_mul_f32 v[56:57], v[0:1], v[56:57] op_sel_hi:[0,1]
	v_pk_mul_f32 v[54:55], v[0:1], v[54:55] op_sel_hi:[0,1]
	v_pk_mul_f32 v[52:53], v[0:1], v[52:53] op_sel_hi:[0,1]
	v_pk_mul_f32 v[50:51], v[0:1], v[50:51] op_sel_hi:[0,1]
	v_pk_mul_f32 v[48:49], v[0:1], v[48:49] op_sel_hi:[0,1]
	v_pk_mul_f32 v[46:47], v[0:1], v[46:47] op_sel_hi:[0,1]
	v_pk_mul_f32 v[44:45], v[0:1], v[44:45] op_sel_hi:[0,1]
	v_pk_mul_f32 v[42:43], v[0:1], v[42:43] op_sel_hi:[0,1]
	v_pk_mul_f32 v[40:41], v[0:1], v[40:41] op_sel_hi:[0,1]
	v_pk_mul_f32 v[38:39], v[0:1], v[38:39] op_sel_hi:[0,1]
	v_pk_mul_f32 v[36:37], v[0:1], v[36:37] op_sel_hi:[0,1]
	v_pk_mul_f32 v[34:35], v[0:1], v[34:35] op_sel_hi:[0,1]
	v_pk_mul_f32 v[32:33], v[0:1], v[32:33] op_sel_hi:[0,1]
	v_pk_mul_f32 v[30:31], v[0:1], v[30:31] op_sel_hi:[0,1]
	v_pk_mul_f32 v[28:29], v[0:1], v[28:29] op_sel_hi:[0,1]
	v_pk_mul_f32 v[26:27], v[0:1], v[26:27] op_sel_hi:[0,1]
	v_pk_mul_f32 v[24:25], v[0:1], v[24:25] op_sel_hi:[0,1]
	v_pk_mul_f32 v[22:23], v[0:1], v[22:23] op_sel_hi:[0,1]
	v_pk_mul_f32 v[20:21], v[0:1], v[20:21] op_sel_hi:[0,1]
	v_pk_mul_f32 v[18:19], v[0:1], v[18:19] op_sel_hi:[0,1]
	v_pk_mul_f32 v[16:17], v[0:1], v[16:17] op_sel_hi:[0,1]
	s_branch .LBB0_154

; #define MFMA32(a, b, c) __builtin_amdgcn_mfma_f32_32x32x16_bf16((a), (b), (c), 0, 0, 0)
; DI f32x16 zero16() { f32x16 z; for (int i = 0; i < 16; ++i) z[i] = 0.f; return z; }
; template <int DQK, int MODE>
; DI void attn_core(const u16* __restrict__ Qg, int ldq, const u16* __restrict__ Kg, int ldk, const u16* __restrict__ Vtg,
;                   const u64* __restrict__ maskg, int q0, float scale, char* smem, int* sflags, f32x16 (&o)[4], float& l_run) {
;     ...
;   for (int it = 0; it < ntiles; ++it, tau += step) {
;     __syncthreads();
;     if (MODE == 2 && it > 0) {
;       if (!(sflags[0] | sflags[1] | sflags[2] | sflags[3] | sflags[4] | sflags[5] | sflags[6] | sflags[7])) break;
;     }
;     if (MODE == 2) gload(tau);
; #pragma unroll
;     for (int i = 0; i < NVK; ++i) {
;       const int v = tid + NT * i, row = v / VPR, c = v % VPR;
;       *(u32x4*)(Ks + row * KSTR + c * 8) = rk[i];
;     }
; #pragma unroll
;     for (int i = 0; i < 2; ++i) {
;       const int v = tid + NT * i, row = v >> 3, c = v & 7;
;       *(u32x4*)(Vs + row * 72 + c * 8) = rv[i];
;     }
;     __syncthreads();
;     if (MODE != 2 && it + 1 < ntiles) gload(tau + step);
;     if (tau * 64 > q0 + 32 * wid + 31) {
;       if (MODE == 2 && lane == 0) sflags[wid] = 1;
;       continue;
;     }
;     u64 mbits = 0;
;     if (MODE == 1) mbits = maskg[(long)qrow * 64 + tau] >> (8 * hh);
;     f32x16 s[2];
;     s[0] = zero16(); s[1] = zero16();
; #pragma unroll
;     for (int kt = 0; kt < 2; ++kt)
; #pragma unroll
;       for (int ks = 0; ks < NKS; ++ks) {
;         const bf16x8 kf = *(const bf16x8*)(Ks + (32 * kt + krow) * KSTR + ks * 16 + hh * 8);
;         s[kt] = MFMA32(kf, qf[ks], s[kt]);
;       }
.LBB0_169:
	v_add_u32_e32 v0, s14, v220
	v_mad_i64_i32 v[2:3], s[4:5], v0, s95, v[184:185]
	v_add_u32_e32 v0, s14, v219
	s_add_i32 s0, s14, 64
	v_mad_i64_i32 v[4:5], s[4:5], v0, s95, v[186:187]
	v_add_u32_e32 v0, s14, v218
	s_nop 0
	s_waitcnt vmcnt(0)
	ds_write_b128 v221, v[176:179]
	ds_write_b128 v226, v[172:175]
	ds_write_b128 v227, v[168:171]
	ds_write_b128 v228, v[164:167] offset:25600
	ds_write_b128 v229, v[160:163] offset:25600
	s_waitcnt lgkmcnt(0)
	global_load_dwordx4 v[176:179], v[2:3], off
	global_load_dwordx4 v[172:175], v[4:5], off
	v_mad_i64_i32 v[2:3], s[4:5], v0, s95, v[206:207]
	s_ashr_i32 s1, s0, 31
	s_lshl_b64 s[4:5], s[0:1], 1
	global_load_dwordx4 v[168:171], v[2:3], off
	v_lshl_add_u64 v[2:3], v[180:181], 0, s[4:5]
	v_lshl_add_u64 v[4:5], v[182:183], 0, s[4:5]
	global_load_dwordx4 v[164:167], v[2:3], off
	global_load_dwordx4 v[160:163], v[4:5], off
	s_barrier
	v_cmp_le_i32_e32 vcc, s14, v217
	s_and_saveexec_b64 s[4:5], vcc
	s_cbranch_execz .LBB0_175
	v_add_u32_e32 v0, v211, v216
	ds_read_b128 v[10:13], v0
	ds_read_b128 v[198:201], v0 offset:32
	ds_read_b128 v[202:205], v0 offset:64
	ds_read_b128 v[232:235], v0 offset:96
	ds_read_b128 v[236:239], v0 offset:128
	ds_read_b128 v[240:243], v0 offset:160
	s_add_i32 s1, s14, 63
	v_cmp_gt_i32_e32 vcc, s1, v214
	s_waitcnt lgkmcnt(5)
	v_mfma_f32_32x32x16_bf16 v[80:95], v[10:13], v[156:159], 0
	ds_read_b128 v[10:13], v0 offset:192
	s_waitcnt lgkmcnt(5)
	v_mfma_f32_32x32x16_bf16 v[80:95], v[198:201], v[152:155], v[80:95]
	ds_read_b128 v[198:201], v0 offset:224
	s_waitcnt lgkmcnt(5)
	v_mfma_f32_32x32x16_bf16 v[80:95], v[202:205], v[148:151], v[80:95]
	ds_read_b128 v[202:205], v0 offset:256
	s_waitcnt lgkmcnt(5)
	v_mfma_f32_32x32x16_bf16 v[80:95], v[232:235], v[144:147], v[80:95]
	ds_read_b128 v[232:235], v0 offset:288
	s_waitcnt lgkmcnt(5)
	v_mfma_f32_32x32x16_bf16 v[80:95], v[236:239], v[140:143], v[80:95]
	ds_read_b128 v[236:239], v0 offset:320
	s_waitcnt lgkmcnt(5)
	v_mfma_f32_32x32x16_bf16 v[80:95], v[240:243], v[136:139], v[80:95]
	ds_read_b128 v[240:243], v0 offset:352
	s_waitcnt lgkmcnt(5)
	v_mfma_f32_32x32x16_bf16 v[80:95], v[10:13], v[132:135], v[80:95]
	ds_read_b128 v[10:13], v0 offset:12800
	s_waitcnt lgkmcnt(5)
	v_mfma_f32_32x32x16_bf16 v[80:95], v[198:201], v[128:131], v[80:95]
	ds_read_b128 v[198:201], v0 offset:12832
	s_waitcnt lgkmcnt(5)
	v_mfma_f32_32x32x16_bf16 v[80:95], v[202:205], v[124:127], v[80:95]
	ds_read_b128 v[202:205], v0 offset:12864
	s_waitcnt lgkmcnt(5)
	v_mfma_f32_32x32x16_bf16 v[80:95], v[232:235], v[120:123], v[80:95]
	ds_read_b128 v[232:235], v0 offset:12896
	s_waitcnt lgkmcnt(5)
	v_mfma_f32_32x32x16_bf16 v[80:95], v[236:239], v[116:119], v[80:95]
	ds_read_b128 v[236:239], v0 offset:12928
	s_waitcnt lgkmcnt(5)
	v_mfma_f32_32x32x16_bf16 v[80:95], v[240:243], v[112:115], v[80:95]
	ds_read_b128 v[240:243], v0 offset:12960
	s_waitcnt lgkmcnt(5)
	v_mfma_f32_32x32x16_bf16 v[96:111], v[10:13], v[156:159], 0
	ds_read_b128 v[10:13], v0 offset:12992
	s_waitcnt lgkmcnt(5)
	v_mfma_f32_32x32x16_bf16 v[96:111], v[198:201], v[152:155], v[96:111]
	ds_read_b128 v[198:201], v0 offset:13024
	s_waitcnt lgkmcnt(5)
	v_mfma_f32_32x32x16_bf16 v[96:111], v[202:205], v[148:151], v[96:111]
	ds_read_b128 v[202:205], v0 offset:13056
	s_waitcnt lgkmcnt(5)
	v_mfma_f32_32x32x16_bf16 v[96:111], v[232:235], v[144:147], v[96:111]
	ds_read_b128 v[232:235], v0 offset:13088
	s_waitcnt lgkmcnt(5)
	v_mfma_f32_32x32x16_bf16 v[96:111], v[236:239], v[140:143], v[96:111]
	ds_read_b128 v[236:239], v0 offset:13120
	s_waitcnt lgkmcnt(5)
	v_mfma_f32_32x32x16_bf16 v[96:111], v[240:243], v[136:139], v[96:111]
	ds_read_b128 v[240:243], v0 offset:13152
	s_waitcnt lgkmcnt(5)
	v_mfma_f32_32x32x16_bf16 v[96:111], v[10:13], v[132:135], v[96:111]
	s_waitcnt lgkmcnt(4)
	v_mfma_f32_32x32x16_bf16 v[96:111], v[198:201], v[128:131], v[96:111]
	s_waitcnt lgkmcnt(3)
	v_mfma_f32_32x32x16_bf16 v[96:111], v[202:205], v[124:127], v[96:111]
	s_waitcnt lgkmcnt(2)
	v_mfma_f32_32x32x16_bf16 v[96:111], v[232:235], v[120:123], v[96:111]
	s_waitcnt lgkmcnt(1)
	v_mfma_f32_32x32x16_bf16 v[96:111], v[236:239], v[116:119], v[96:111]
	s_waitcnt lgkmcnt(0)
	v_mfma_f32_32x32x16_bf16 v[96:111], v[240:243], v[112:115], v[96:111]
	s_and_saveexec_b64 s[6:7], vcc
	s_cbranch_execz .LBB0_172
; template <int DQK, int MODE>
; DI void attn_core(const u16* __restrict__ Qg, int ldq, const u16* __restrict__ Kg, int ldk, const u16* __restrict__ Vtg,
;                   const u64* __restrict__ maskg, int q0, float scale, char* smem, int* sflags, f32x16 (&o)[4], float& l_run) {
;     ...
;       const bool need_mask = (MODE == 1) || (tau * 64 + 63 > q0 + 32 * wid);
;       float mx = -1e30f;
;       if (need_mask) {
; #pragma unroll
;         for (int kt = 0; kt < 2; ++kt)
; #pragma unroll
;           for (int i = 0; i < 16; ++i) {
;             bool valid;
;             if (MODE == 1) valid = (mbits >> (32 * kt + 16 * (i >> 3) + (i & 7))) & 1ull;
;             else valid = (kbase + 32 * kt + 16 * (i >> 3) + (i & 7)) <= qrow;
;             s[kt][i] = valid ? s[kt][i] : -1e30f;
;           }
	v_add_u32_e32 v0, s14, v215
	v_cmp_le_i32_e32 vcc, v0, v213
	v_add_u32_e32 v2, 2, v0
	s_nop 0
	v_cndmask_b32_e32 v80, v225, v80, vcc
	v_cmp_lt_i32_e32 vcc, v0, v213
	s_nop 1
	v_cndmask_b32_e32 v81, v225, v81, vcc
	v_cmp_le_i32_e32 vcc, v2, v213
	v_add_u32_e32 v2, 3, v0
	s_nop 0
	v_cndmask_b32_e32 v82, v225, v82, vcc
	v_cmp_le_i32_e32 vcc, v2, v213
	v_add_u32_e32 v2, 4, v0
	s_nop 0
	v_cndmask_b32_e32 v83, v225, v83, vcc
	v_cmp_le_i32_e32 vcc, v2, v213
	v_add_u32_e32 v2, 5, v0
	s_nop 0
	v_cndmask_b32_e32 v84, v225, v84, vcc
	v_cmp_le_i32_e32 vcc, v2, v213
	v_add_u32_e32 v2, 6, v0
	s_nop 0
	v_cndmask_b32_e32 v85, v225, v85, vcc
	v_cmp_le_i32_e32 vcc, v2, v213
	v_add_u32_e32 v2, 7, v0
	s_nop 0
	v_cndmask_b32_e32 v86, v225, v86, vcc
	v_cmp_le_i32_e32 vcc, v2, v213
	v_add_u32_e32 v2, 16, v0
	s_nop 0
	v_cndmask_b32_e32 v87, v225, v87, vcc
	v_cmp_le_i32_e32 vcc, v2, v213
	v_add_u32_e32 v2, 17, v0
	s_nop 0
	v_cndmask_b32_e32 v88, v225, v88, vcc
	v_cmp_le_i32_e32 vcc, v2, v213
	v_add_u32_e32 v2, 18, v0
	s_nop 0
	v_cndmask_b32_e32 v89, v225, v89, vcc
	v_cmp_le_i32_e32 vcc, v2, v213
	v_add_u32_e32 v2, 19, v0
	s_nop 0
	v_cndmask_b32_e32 v90, v225, v90, vcc
	v_cmp_le_i32_e32 vcc, v2, v213
	v_add_u32_e32 v2, 20, v0
	s_nop 0
	v_cndmask_b32_e32 v91, v225, v91, vcc
	v_cmp_le_i32_e32 vcc, v2, v213
	v_add_u32_e32 v2, 21, v0
	s_nop 0
	v_cndmask_b32_e32 v92, v225, v92, vcc
	v_cmp_le_i32_e32 vcc, v2, v213
	v_add_u32_e32 v2, 22, v0
	s_nop 0
	v_cndmask_b32_e32 v93, v225, v93, vcc
	v_cmp_le_i32_e32 vcc, v2, v213
	v_add_u32_e32 v2, 23, v0
	s_nop 0
	v_cndmask_b32_e32 v94, v225, v94, vcc
	v_cmp_le_i32_e32 vcc, v2, v213
	v_add_u32_e32 v2, 32, v0
	s_nop 0
	v_cndmask_b32_e32 v95, v225, v95, vcc
	v_cmp_le_i32_e32 vcc, v2, v213
	v_add_u32_e32 v2, 33, v0
	s_nop 0
	v_cndmask_b32_e32 v96, v225, v96, vcc
	v_cmp_le_i32_e32 vcc, v2, v213
	v_add_u32_e32 v2, 34, v0
	s_nop 0
	v_cndmask_b32_e32 v97, v225, v97, vcc
	v_cmp_le_i32_e32 vcc, v2, v213
	v_add_u32_e32 v2, 35, v0
	s_nop 0
	v_cndmask_b32_e32 v98, v225, v98, vcc
	v_cmp_le_i32_e32 vcc, v2, v213
	v_add_u32_e32 v2, 36, v0
	s_nop 0
	v_cndmask_b32_e32 v99, v225, v99, vcc
	v_cmp_le_i32_e32 vcc, v2, v213
	v_add_u32_e32 v2, 37, v0
	s_nop 0
	v_cndmask_b32_e32 v100, v225, v100, vcc
	v_cmp_le_i32_e32 vcc, v2, v213
	v_add_u32_e32 v2, 38, v0
	s_nop 0
	v_cndmask_b32_e32 v101, v225, v101, vcc
	v_cmp_le_i32_e32 vcc, v2, v213
	v_add_u32_e32 v2, 39, v0
	s_nop 0
	v_cndmask_b32_e32 v102, v225, v102, vcc
	v_cmp_le_i32_e32 vcc, v2, v213
	v_add_u32_e32 v2, 48, v0
	s_nop 0
	v_cndmask_b32_e32 v103, v225, v103, vcc
	v_cmp_le_i32_e32 vcc, v2, v213
	v_add_u32_e32 v2, 49, v0
	s_nop 0
	v_cndmask_b32_e32 v104, v225, v104, vcc
	v_cmp_le_i32_e32 vcc, v2, v213
	v_add_u32_e32 v2, 50, v0
	s_nop 0
	v_cndmask_b32_e32 v105, v225, v105, vcc
	v_cmp_le_i32_e32 vcc, v2, v213
	v_add_u32_e32 v2, 51, v0
	s_nop 0
	v_cndmask_b32_e32 v106, v225, v106, vcc
	v_cmp_le_i32_e32 vcc, v2, v213
	v_add_u32_e32 v2, 52, v0
	s_nop 0
	v_cndmask_b32_e32 v107, v225, v107, vcc
	v_cmp_le_i32_e32 vcc, v2, v213
	v_add_u32_e32 v2, 53, v0
	s_nop 0
	v_cndmask_b32_e32 v108, v225, v108, vcc
	v_cmp_le_i32_e32 vcc, v2, v213
	v_add_u32_e32 v2, 54, v0
	v_add_u32_e32 v0, 55, v0
	v_cndmask_b32_e32 v109, v225, v109, vcc
	v_cmp_le_i32_e32 vcc, v2, v213
	s_nop 1
	v_cndmask_b32_e32 v110, v225, v110, vcc
	v_cmp_le_i32_e32 vcc, v0, v213
	s_nop 1
	v_cndmask_b32_e32 v111, v225, v111, vcc

; #define MFMA32(a, b, c) __builtin_amdgcn_mfma_f32_32x32x16_bf16((a), (b), (c), 0, 0, 0)
; DI f32x16 zero16() { f32x16 z; for (int i = 0; i < 16; ++i) z[i] = 0.f; return z; }
; template <int DQK, int MODE>
; DI void attn_core(const u16* __restrict__ Qg, int ldq, const u16* __restrict__ Kg, int ldk, const u16* __restrict__ Vtg,
;                   const u64* __restrict__ maskg, int q0, float scale, char* smem, int* sflags, f32x16 (&o)[4], float& l_run) {
;     ...
;   for (int it = 0; it < ntiles; ++it, tau += step) {
;     __syncthreads();
;     if (MODE == 2 && it > 0) {
;       if (!(sflags[0] | sflags[1] | sflags[2] | sflags[3] | sflags[4] | sflags[5] | sflags[6] | sflags[7])) break;
;     }
;     if (MODE == 2) gload(tau);
; #pragma unroll
;     for (int i = 0; i < NVK; ++i) {
;       const int v = tid + NT * i, row = v / VPR, c = v % VPR;
;       *(u32x4*)(Ks + row * KSTR + c * 8) = rk[i];
;     }
; #pragma unroll
;     for (int i = 0; i < 2; ++i) {
;       const int v = tid + NT * i, row = v >> 3, c = v & 7;
;       *(u32x4*)(Vs + row * 72 + c * 8) = rv[i];
;     }
;     __syncthreads();
;     if (MODE != 2 && it + 1 < ntiles) gload(tau + step);
;     if (tau * 64 > q0 + 32 * wid + 31) {
;       if (MODE == 2 && lane == 0) sflags[wid] = 1;
;       continue;
;     }
;     u64 mbits = 0;
;     if (MODE == 1) mbits = maskg[(long)qrow * 64 + tau] >> (8 * hh);
;     f32x16 s[2];
;     s[0] = zero16(); s[1] = zero16();
; #pragma unroll
;     for (int kt = 0; kt < 2; ++kt)
; #pragma unroll
;       for (int ks = 0; ks < NKS; ++ks) {
;         const bf16x8 kf = *(const bf16x8*)(Ks + (32 * kt + krow) * KSTR + ks * 16 + hh * 8);
;         s[kt] = MFMA32(kf, qf[ks], s[kt]);
;       }
;     const int kbase = tau * 64 + 8 * hh;
;     if (MODE == 0 || MODE == 1) {
;       const bool need_mask = (MODE == 1) || (tau * 64 + 63 > q0 + 32 * wid);
;       float mx = -1e30f;
;       if (need_mask) {
; #pragma unroll
;         for (int kt = 0; kt < 2; ++kt)
; #pragma unroll
;           for (int i = 0; i < 16; ++i) {
;             bool valid;
;             if (MODE == 1) valid = (mbits >> (32 * kt + 16 * (i >> 3) + (i & 7))) & 1ull;
;             else valid = (kbase + 32 * kt + 16 * (i >> 3) + (i & 7)) <= qrow;
;             s[kt][i] = valid ? s[kt][i] : -1e30f;
;           }
.LBB0_240:
	s_add_i32 s4, s15, 64
	v_add_u32_e32 v0, s15, v156
	v_mad_i64_i32 v[2:3], s[6:7], v0, s75, v[146:147]
	s_ashr_i32 s5, s4, 31
	s_lshl_b64 s[6:7], s[4:5], 1
	s_waitcnt lgkmcnt(0)
	s_nop 0
	s_waitcnt vmcnt(0)
	ds_write_b128 v157, v[128:131]
	ds_write_b128 v158, v[136:139] offset:9216
	ds_write_b128 v159, v[132:135] offset:9216
	s_waitcnt lgkmcnt(0)
	global_load_dwordx4 v[128:131], v[2:3], off offset:1024
	v_lshl_add_u64 v[2:3], v[142:143], 0, s[6:7]
	v_lshl_add_u64 v[4:5], v[144:145], 0, s[6:7]
	global_load_dwordx4 v[136:139], v[2:3], off
	global_load_dwordx4 v[132:135], v[4:5], off
	s_barrier
	v_cmp_le_i32_e32 vcc, s15, v155
	s_and_saveexec_b64 s[6:7], vcc
	s_cbranch_execz .LBB0_246
	v_add_u32_e32 v0, v149, v154
	ds_read_b128 v[10:13], v0
	ds_read_b128 v[162:165], v0 offset:32
	ds_read_b128 v[166:169], v0 offset:64
	ds_read_b128 v[170:173], v0 offset:96
	ds_read_b128 v[174:177], v0 offset:4608
	ds_read_b128 v[178:181], v0 offset:4640
	s_add_i32 s5, s15, 63
	v_cmp_gt_i32_e32 vcc, s5, v152
	s_waitcnt lgkmcnt(5)
	v_mfma_f32_32x32x16_bf16 v[96:111], v[10:13], v[124:127], 0
	ds_read_b128 v[10:13], v0 offset:4672
	s_waitcnt lgkmcnt(5)
	v_mfma_f32_32x32x16_bf16 v[96:111], v[162:165], v[120:123], v[96:111]
	ds_read_b128 v[162:165], v0 offset:4704
	s_waitcnt lgkmcnt(5)
	v_mfma_f32_32x32x16_bf16 v[96:111], v[166:169], v[116:119], v[96:111]
	s_waitcnt lgkmcnt(4)
	v_mfma_f32_32x32x16_bf16 v[96:111], v[170:173], v[112:115], v[96:111]
	s_waitcnt lgkmcnt(3)
	v_mfma_f32_32x32x16_bf16 v[80:95], v[174:177], v[124:127], 0
	s_waitcnt lgkmcnt(2)
	v_mfma_f32_32x32x16_bf16 v[80:95], v[178:181], v[120:123], v[80:95]
	s_waitcnt lgkmcnt(1)
	v_mfma_f32_32x32x16_bf16 v[80:95], v[10:13], v[116:119], v[80:95]
	s_waitcnt lgkmcnt(0)
	v_mfma_f32_32x32x16_bf16 v[80:95], v[162:165], v[112:115], v[80:95]
	s_and_saveexec_b64 s[8:9], vcc
	s_cbranch_execz .LBB0_243
	v_add_u32_e32 v0, s15, v153
	v_cmp_le_i32_e32 vcc, v0, v151
	v_add_u32_e32 v2, 2, v0
	s_nop 0
	v_cndmask_b32_e32 v96, v225, v96, vcc
	v_cmp_lt_i32_e32 vcc, v0, v151
	s_nop 1
	v_cndmask_b32_e32 v97, v225, v97, vcc
	v_cmp_le_i32_e32 vcc, v2, v151
	v_add_u32_e32 v2, 3, v0
	s_nop 0
	v_cndmask_b32_e32 v98, v225, v98, vcc
	v_cmp_le_i32_e32 vcc, v2, v151
	v_add_u32_e32 v2, 4, v0
	s_nop 0
	v_cndmask_b32_e32 v99, v225, v99, vcc
	v_cmp_le_i32_e32 vcc, v2, v151
	v_add_u32_e32 v2, 5, v0
	s_nop 0
	v_cndmask_b32_e32 v100, v225, v100, vcc
	v_cmp_le_i32_e32 vcc, v2, v151
	v_add_u32_e32 v2, 6, v0
	s_nop 0
	v_cndmask_b32_e32 v101, v225, v101, vcc
	v_cmp_le_i32_e32 vcc, v2, v151
	v_add_u32_e32 v2, 7, v0
	s_nop 0
	v_cndmask_b32_e32 v102, v225, v102, vcc
	v_cmp_le_i32_e32 vcc, v2, v151
	v_add_u32_e32 v2, 16, v0
	s_nop 0
	v_cndmask_b32_e32 v103, v225, v103, vcc
	v_cmp_le_i32_e32 vcc, v2, v151
	v_add_u32_e32 v2, 17, v0
	s_nop 0
	v_cndmask_b32_e32 v104, v225, v104, vcc
	v_cmp_le_i32_e32 vcc, v2, v151
	v_add_u32_e32 v2, 18, v0
	s_nop 0
	v_cndmask_b32_e32 v105, v225, v105, vcc
	v_cmp_le_i32_e32 vcc, v2, v151
	v_add_u32_e32 v2, 19, v0
	s_nop 0
	v_cndmask_b32_e32 v106, v225, v106, vcc
	v_cmp_le_i32_e32 vcc, v2, v151
	v_add_u32_e32 v2, 20, v0
	s_nop 0
	v_cndmask_b32_e32 v107, v225, v107, vcc
	v_cmp_le_i32_e32 vcc, v2, v151
	v_add_u32_e32 v2, 21, v0
	s_nop 0
	v_cndmask_b32_e32 v108, v225, v108, vcc
	v_cmp_le_i32_e32 vcc, v2, v151
	v_add_u32_e32 v2, 22, v0
	s_nop 0
	v_cndmask_b32_e32 v109, v225, v109, vcc
	v_cmp_le_i32_e32 vcc, v2, v151
	v_add_u32_e32 v2, 23, v0
	s_nop 0
	v_cndmask_b32_e32 v110, v225, v110, vcc
	v_cmp_le_i32_e32 vcc, v2, v151
	v_add_u32_e32 v2, 32, v0
	s_nop 0
	v_cndmask_b32_e32 v111, v225, v111, vcc
	v_cmp_le_i32_e32 vcc, v2, v151
	v_add_u32_e32 v2, 33, v0
	s_nop 0
	v_cndmask_b32_e32 v80, v225, v80, vcc
	v_cmp_le_i32_e32 vcc, v2, v151
	v_add_u32_e32 v2, 34, v0
	s_nop 0
	v_cndmask_b32_e32 v81, v225, v81, vcc
	v_cmp_le_i32_e32 vcc, v2, v151
	v_add_u32_e32 v2, 35, v0
	s_nop 0
	v_cndmask_b32_e32 v82, v225, v82, vcc
	v_cmp_le_i32_e32 vcc, v2, v151
	v_add_u32_e32 v2, 36, v0
	s_nop 0
	v_cndmask_b32_e32 v83, v225, v83, vcc
	v_cmp_le_i32_e32 vcc, v2, v151
	v_add_u32_e32 v2, 37, v0
	s_nop 0
	v_cndmask_b32_e32 v84, v225, v84, vcc
	v_cmp_le_i32_e32 vcc, v2, v151
	v_add_u32_e32 v2, 38, v0
	s_nop 0
	v_cndmask_b32_e32 v85, v225, v85, vcc
	v_cmp_le_i32_e32 vcc, v2, v151
	v_add_u32_e32 v2, 39, v0
	s_nop 0
	v_cndmask_b32_e32 v86, v225, v86, vcc
	v_cmp_le_i32_e32 vcc, v2, v151
	v_add_u32_e32 v2, 48, v0
	s_nop 0
	v_cndmask_b32_e32 v87, v225, v87, vcc
	v_cmp_le_i32_e32 vcc, v2, v151
	v_add_u32_e32 v2, 49, v0
	s_nop 0
	v_cndmask_b32_e32 v88, v225, v88, vcc
	v_cmp_le_i32_e32 vcc, v2, v151
	v_add_u32_e32 v2, 50, v0
	s_nop 0
	v_cndmask_b32_e32 v89, v225, v89, vcc
	v_cmp_le_i32_e32 vcc, v2, v151
	v_add_u32_e32 v2, 51, v0
	s_nop 0
	v_cndmask_b32_e32 v90, v225, v90, vcc
	v_cmp_le_i32_e32 vcc, v2, v151
	v_add_u32_e32 v2, 52, v0
	s_nop 0
	v_cndmask_b32_e32 v91, v225, v91, vcc
	v_cmp_le_i32_e32 vcc, v2, v151
	v_add_u32_e32 v2, 53, v0
	s_nop 0
	v_cndmask_b32_e32 v92, v225, v92, vcc
	v_cmp_le_i32_e32 vcc, v2, v151
	v_add_u32_e32 v2, 54, v0
	v_add_u32_e32 v0, 55, v0
	v_cndmask_b32_e32 v93, v225, v93, vcc
	v_cmp_le_i32_e32 vcc, v2, v151
	s_nop 1
	v_cndmask_b32_e32 v94, v225, v94, vcc
	v_cmp_le_i32_e32 vcc, v0, v151
	s_nop 1
	v_cndmask_b32_e32 v95, v225, v95, vcc

; #define MFMA32(a, b, c) __builtin_amdgcn_mfma_f32_32x32x16_bf16((a), (b), (c), 0, 0, 0)
; DI f32x16 zero16() { f32x16 z; for (int i = 0; i < 16; ++i) z[i] = 0.f; return z; }
; template <int DQK, int MODE>
; DI void attn_core(const u16* __restrict__ Qg, int ldq, const u16* __restrict__ Kg, int ldk, const u16* __restrict__ Vtg,
;                   const u64* __restrict__ maskg, int q0, float scale, char* smem, int* sflags, f32x16 (&o)[4], float& l_run) {
;     ...
;   for (int it = 0; it < ntiles; ++it, tau += step) {
;     __syncthreads();
;     if (MODE == 2 && it > 0) {
;       if (!(sflags[0] | sflags[1] | sflags[2] | sflags[3] | sflags[4] | sflags[5] | sflags[6] | sflags[7])) break;
;     }
;     if (MODE == 2) gload(tau);
; #pragma unroll
;     for (int i = 0; i < NVK; ++i) {
;       const int v = tid + NT * i, row = v / VPR, c = v % VPR;
;       *(u32x4*)(Ks + row * KSTR + c * 8) = rk[i];
;     }
; #pragma unroll
;     for (int i = 0; i < 2; ++i) {
;       const int v = tid + NT * i, row = v >> 3, c = v & 7;
;       *(u32x4*)(Vs + row * 72 + c * 8) = rv[i];
;     }
;     __syncthreads();
;     if (MODE != 2 && it + 1 < ntiles) gload(tau + step);
;     if (tau * 64 > q0 + 32 * wid + 31) {
;       if (MODE == 2 && lane == 0) sflags[wid] = 1;
;       continue;
;     }
;     u64 mbits = 0;
;     if (MODE == 1) mbits = maskg[(long)qrow * 64 + tau] >> (8 * hh);
;     f32x16 s[2];
;     s[0] = zero16(); s[1] = zero16();
; #pragma unroll
;     for (int kt = 0; kt < 2; ++kt)
; #pragma unroll
;       for (int ks = 0; ks < NKS; ++ks) {
;         const bf16x8 kf = *(const bf16x8*)(Ks + (32 * kt + krow) * KSTR + ks * 16 + hh * 8);
;         s[kt] = MFMA32(kf, qf[ks], s[kt]);
;       }
;     const int kbase = tau * 64 + 8 * hh;
;     if (MODE == 0 || MODE == 1) {
;       const bool need_mask = (MODE == 1) || (tau * 64 + 63 > q0 + 32 * wid);
;       float mx = -1e30f;
;       if (need_mask) {
; #pragma unroll
;         for (int kt = 0; kt < 2; ++kt)
; #pragma unroll
;           for (int i = 0; i < 16; ++i) {
;             bool valid;
;             if (MODE == 1) valid = (mbits >> (32 * kt + 16 * (i >> 3) + (i & 7))) & 1ull;
;             else valid = (kbase + 32 * kt + 16 * (i >> 3) + (i & 7)) <= qrow;
;             s[kt][i] = valid ? s[kt][i] : -1e30f;
;           }
.LBB0_258:
	s_add_i32 s0, s7, 64
	v_add_u32_e32 v0, s7, v158
	v_mad_i64_i32 v[2:3], s[2:3], v0, s75, v[150:151]
	s_ashr_i32 s1, s0, 31
	s_lshl_b64 s[2:3], s[0:1], 1
	s_nop 0
	s_waitcnt vmcnt(0)
	ds_write_b128 v159, v[128:131]
	ds_write_b128 v160, v[136:139] offset:9216
	ds_write_b128 v161, v[132:135] offset:9216
	s_waitcnt lgkmcnt(0)
	global_load_dwordx4 v[128:131], v[2:3], off offset:1152
	v_lshl_add_u64 v[2:3], v[146:147], 0, s[2:3]
	v_lshl_add_u64 v[4:5], v[148:149], 0, s[2:3]
	global_load_dwordx4 v[136:139], v[2:3], off
	global_load_dwordx4 v[132:135], v[4:5], off
	s_barrier
	v_cmp_le_i32_e32 vcc, s7, v157
	s_and_saveexec_b64 s[2:3], vcc
	s_cbranch_execz .LBB0_264
	v_add_u32_e32 v0, v142, v156
	ds_read_b128 v[10:13], v0
	ds_read_b128 v[164:167], v0 offset:32
	ds_read_b128 v[168:171], v0 offset:64
	ds_read_b128 v[172:175], v0 offset:96
	ds_read_b128 v[176:179], v0 offset:4608
	ds_read_b128 v[180:183], v0 offset:4640
	s_add_i32 s1, s7, 63
	v_cmp_gt_i32_e32 vcc, s1, v154
	s_waitcnt lgkmcnt(5)
	v_mfma_f32_32x32x16_bf16 v[96:111], v[10:13], v[124:127], 0
	ds_read_b128 v[10:13], v0 offset:4672
	s_waitcnt lgkmcnt(5)
	v_mfma_f32_32x32x16_bf16 v[96:111], v[164:167], v[120:123], v[96:111]
	ds_read_b128 v[164:167], v0 offset:4704
	s_waitcnt lgkmcnt(5)
	v_mfma_f32_32x32x16_bf16 v[96:111], v[168:171], v[116:119], v[96:111]
	s_waitcnt lgkmcnt(4)
	v_mfma_f32_32x32x16_bf16 v[96:111], v[172:175], v[112:115], v[96:111]
	s_waitcnt lgkmcnt(3)
	v_mfma_f32_32x32x16_bf16 v[80:95], v[176:179], v[124:127], 0
	s_waitcnt lgkmcnt(2)
	v_mfma_f32_32x32x16_bf16 v[80:95], v[180:183], v[120:123], v[80:95]
	s_waitcnt lgkmcnt(1)
	v_mfma_f32_32x32x16_bf16 v[80:95], v[10:13], v[116:119], v[80:95]
	s_waitcnt lgkmcnt(0)
	v_mfma_f32_32x32x16_bf16 v[80:95], v[164:167], v[112:115], v[80:95]
	s_and_saveexec_b64 s[4:5], vcc
	s_cbranch_execz .LBB0_261
	v_add_u32_e32 v0, s7, v155
	v_cmp_le_i32_e32 vcc, v0, v153
	v_add_u32_e32 v2, 2, v0
	s_nop 0
	v_cndmask_b32_e32 v96, v225, v96, vcc
	v_cmp_lt_i32_e32 vcc, v0, v153
	s_nop 1
	v_cndmask_b32_e32 v97, v225, v97, vcc
	v_cmp_le_i32_e32 vcc, v2, v153
	v_add_u32_e32 v2, 3, v0
	s_nop 0
	v_cndmask_b32_e32 v98, v225, v98, vcc
	v_cmp_le_i32_e32 vcc, v2, v153
	v_add_u32_e32 v2, 4, v0
	s_nop 0
	v_cndmask_b32_e32 v99, v225, v99, vcc
	v_cmp_le_i32_e32 vcc, v2, v153
	v_add_u32_e32 v2, 5, v0
	s_nop 0
	v_cndmask_b32_e32 v100, v225, v100, vcc
	v_cmp_le_i32_e32 vcc, v2, v153
	v_add_u32_e32 v2, 6, v0
	s_nop 0
	v_cndmask_b32_e32 v101, v225, v101, vcc
	v_cmp_le_i32_e32 vcc, v2, v153
	v_add_u32_e32 v2, 7, v0
	s_nop 0
	v_cndmask_b32_e32 v102, v225, v102, vcc
	v_cmp_le_i32_e32 vcc, v2, v153
	v_add_u32_e32 v2, 16, v0
	s_nop 0
	v_cndmask_b32_e32 v103, v225, v103, vcc
	v_cmp_le_i32_e32 vcc, v2, v153
	v_add_u32_e32 v2, 17, v0
	s_nop 0
	v_cndmask_b32_e32 v104, v225, v104, vcc
	v_cmp_le_i32_e32 vcc, v2, v153
	v_add_u32_e32 v2, 18, v0
	s_nop 0
	v_cndmask_b32_e32 v105, v225, v105, vcc
	v_cmp_le_i32_e32 vcc, v2, v153
	v_add_u32_e32 v2, 19, v0
	s_nop 0
	v_cndmask_b32_e32 v106, v225, v106, vcc
	v_cmp_le_i32_e32 vcc, v2, v153
	v_add_u32_e32 v2, 20, v0
	s_nop 0
	v_cndmask_b32_e32 v107, v225, v107, vcc
	v_cmp_le_i32_e32 vcc, v2, v153
	v_add_u32_e32 v2, 21, v0
	s_nop 0
	v_cndmask_b32_e32 v108, v225, v108, vcc
	v_cmp_le_i32_e32 vcc, v2, v153
	v_add_u32_e32 v2, 22, v0
	s_nop 0
	v_cndmask_b32_e32 v109, v225, v109, vcc
	v_cmp_le_i32_e32 vcc, v2, v153
	v_add_u32_e32 v2, 23, v0
	s_nop 0
	v_cndmask_b32_e32 v110, v225, v110, vcc
	v_cmp_le_i32_e32 vcc, v2, v153
	v_add_u32_e32 v2, 32, v0
	s_nop 0
	v_cndmask_b32_e32 v111, v225, v111, vcc
	v_cmp_le_i32_e32 vcc, v2, v153
	v_add_u32_e32 v2, 33, v0
	s_nop 0
	v_cndmask_b32_e32 v80, v225, v80, vcc
	v_cmp_le_i32_e32 vcc, v2, v153
	v_add_u32_e32 v2, 34, v0
	s_nop 0
	v_cndmask_b32_e32 v81, v225, v81, vcc
	v_cmp_le_i32_e32 vcc, v2, v153
	v_add_u32_e32 v2, 35, v0
	s_nop 0
	v_cndmask_b32_e32 v82, v225, v82, vcc
	v_cmp_le_i32_e32 vcc, v2, v153
	v_add_u32_e32 v2, 36, v0
	s_nop 0
	v_cndmask_b32_e32 v83, v225, v83, vcc
	v_cmp_le_i32_e32 vcc, v2, v153
	v_add_u32_e32 v2, 37, v0
	s_nop 0
	v_cndmask_b32_e32 v84, v225, v84, vcc
	v_cmp_le_i32_e32 vcc, v2, v153
	v_add_u32_e32 v2, 38, v0
	s_nop 0
	v_cndmask_b32_e32 v85, v225, v85, vcc
	v_cmp_le_i32_e32 vcc, v2, v153
	v_add_u32_e32 v2, 39, v0
	s_nop 0
	v_cndmask_b32_e32 v86, v225, v86, vcc
	v_cmp_le_i32_e32 vcc, v2, v153
	v_add_u32_e32 v2, 48, v0
	s_nop 0
	v_cndmask_b32_e32 v87, v225, v87, vcc
	v_cmp_le_i32_e32 vcc, v2, v153
	v_add_u32_e32 v2, 49, v0
	s_nop 0
	v_cndmask_b32_e32 v88, v225, v88, vcc
	v_cmp_le_i32_e32 vcc, v2, v153
	v_add_u32_e32 v2, 50, v0
	s_nop 0
	v_cndmask_b32_e32 v89, v225, v89, vcc
	v_cmp_le_i32_e32 vcc, v2, v153
	v_add_u32_e32 v2, 51, v0
	s_nop 0
	v_cndmask_b32_e32 v90, v225, v90, vcc
	v_cmp_le_i32_e32 vcc, v2, v153
	v_add_u32_e32 v2, 52, v0
	s_nop 0
	v_cndmask_b32_e32 v91, v225, v91, vcc
	v_cmp_le_i32_e32 vcc, v2, v153
	v_add_u32_e32 v2, 53, v0
	s_nop 0
	v_cndmask_b32_e32 v92, v225, v92, vcc
	v_cmp_le_i32_e32 vcc, v2, v153
	v_add_u32_e32 v2, 54, v0
	v_add_u32_e32 v0, 55, v0
	v_cndmask_b32_e32 v93, v225, v93, vcc
	v_cmp_le_i32_e32 vcc, v2, v153
	s_nop 1
	v_cndmask_b32_e32 v94, v225, v94, vcc
	v_cmp_le_i32_e32 vcc, v0, v153
	s_nop 1
	v_cndmask_b32_e32 v95, v225, v95, vcc
